# P6 EpiAct SS1 hoist + P7 EpiDown final normalisation: row statistics via 16 pipelined sc1 loads with counted waits instead of 16 dependent returning atomics
# speedup vs baseline: 1.0055x; 1.0055x over previous
; __device__ __forceinline__ float rstd_of(float ss) { return __builtin_amdgcn_rsqf(ss * (1.0f / DM) + EPS); }
; __device__ __forceinline__ float atomic_read_f32(float* p) { return __hip_atomic_fetch_add(p, 0.0f, __ATOMIC_RELAXED, __HIP_MEMORY_SCOPE_AGENT); }
;     __device__ __forceinline__ void operator()(pg8::f32x4 (&acc)[2][2][4][2], const Unit& u, int wr, int wc, int fr, int fq) const {
;     ...
;         pg8::f32x4 gn[2];
; #pragma unroll
;         for (int bj = 0; bj < 2; ++bj) gn[bj] = *(const pg8::f32x4*)(gain + cbase + bj * HALF);
; #pragma unroll
;         for (int ai = 0; ai < 2; ++ai)
; #pragma unroll
;             for (int m = 0; m < 4; ++m)
; #pragma unroll
;                 for (int p = 0; p < 2; ++p) { const int row = row0 + ai * HALF + m * 16 + 8 * p + rr; float s = 0.f; if (sl == 0) s = atomic_read_f32(SS2 + row); const float rs = rstd_of(__shfl(s, lane & ~7));
; #pragma unroll
;                     for (int bj = 0; bj < 2; ++bj) *(pg8::f32x4*)(YO + (size_t)row * DM + cbase + bj * HALF) = acc[ai][bj][m][p] * rs * gn[bj]; }
.LBB0_1101:
	v_readlane_b32 s64, v238, 29
	v_readlane_b32 s78, v238, 43
	v_readlane_b32 s79, v238, 44
	v_mov_b32_e32 v176, 0
	v_mov_b32_e32 v177, 0
	v_lshl_add_u64 v[2:3], v[150:151], 2, s[78:79]
	global_load_dwordx4 v[6:9], v[2:3], off
	s_waitcnt lgkmcnt(0)
	global_load_dwordx4 v[2:5], v[2:3], off offset:512
	v_readlane_b32 s65, v238, 30
	v_readlane_b32 s66, v238, 31
	v_readlane_b32 s67, v238, 32
	v_readlane_b32 s68, v238, 33
	v_readlane_b32 s69, v238, 34
	v_readlane_b32 s70, v238, 35
	v_readlane_b32 s71, v238, 36
	v_readlane_b32 s72, v238, 37
	v_readlane_b32 s73, v238, 38
	v_readlane_b32 s74, v238, 39
	v_readlane_b32 s75, v238, 40
	v_readlane_b32 s76, v238, 41
	v_readlane_b32 s77, v238, 42
	v_lshl_add_u64 v[228:229], v[152:153], 2, s[14:15]
	global_load_dword v194, v[228:229], off sc1
	global_load_dword v195, v[228:229], off offset:32 sc1
	global_load_dword v196, v[228:229], off offset:64 sc1
	global_load_dword v197, v[228:229], off offset:96 sc1
	global_load_dword v198, v[228:229], off offset:128 sc1
	global_load_dword v199, v[228:229], off offset:160 sc1
	global_load_dword v200, v[228:229], off offset:192 sc1
	global_load_dword v201, v[228:229], off offset:224 sc1
	global_load_dword v202, v[228:229], off offset:512 sc1
	global_load_dword v203, v[228:229], off offset:544 sc1
	global_load_dword v204, v[228:229], off offset:576 sc1
	global_load_dword v205, v[228:229], off offset:608 sc1
	global_load_dword v206, v[228:229], off offset:640 sc1
	global_load_dword v207, v[228:229], off offset:672 sc1
	global_load_dword v208, v[228:229], off offset:704 sc1
	global_load_dword v209, v[228:229], off offset:736 sc1
	s_waitcnt vmcnt(15)
	v_mov_b32_e32 v177, v194
	v_lshlrev_b64 v[180:181], 12, v[152:153]
	v_lshl_add_u64 v[180:181], s[48:49], 0, v[180:181]
	v_lshl_add_u64 v[180:181], v[150:151], 2, v[180:181]
	s_waitcnt lgkmcnt(0)
	v_fmamk_f32 v177, v177, 0x3a800000, v172
	v_rsq_f32_e32 v178, v177
	s_nop 0
	v_pk_mul_f32 v[128:129], v[128:129], v[178:179] op_sel_hi:[1,0]
	v_pk_mul_f32 v[124:125], v[124:125], v[178:179] op_sel_hi:[1,0]
	v_pk_mul_f32 v[126:127], v[126:127], v[178:179] op_sel_hi:[1,0]
	v_pk_mul_f32 v[178:179], v[122:123], v[178:179] op_sel_hi:[1,0]
	v_pk_mul_f32 v[124:125], v[8:9], v[124:125]
	v_pk_mul_f32 v[122:123], v[6:7], v[128:129]
	global_store_dwordx4 v[180:181], v[122:125], off
	s_nop 1
	v_pk_mul_f32 v[124:125], v[4:5], v[178:179]
	v_pk_mul_f32 v[122:123], v[2:3], v[126:127]
	global_store_dwordx4 v[180:181], v[122:125], off offset:512
	s_nop 0
	s_waitcnt vmcnt(16)
	v_mov_b32_e32 v122, v195
	v_lshlrev_b64 v[124:125], 12, v[156:157]
	v_lshl_add_u64 v[124:125], s[48:49], 0, v[124:125]
	v_lshl_add_u64 v[124:125], v[150:151], 2, v[124:125]
	s_waitcnt lgkmcnt(0)
	v_fmamk_f32 v122, v122, 0x3a800000, v172
	v_rsq_f32_e32 v122, v122
	s_nop 0
	v_pk_mul_f32 v[116:117], v[116:117], v[122:123] op_sel_hi:[1,0]
	v_pk_mul_f32 v[118:119], v[118:119], v[122:123] op_sel_hi:[1,0]
	v_pk_mul_f32 v[126:127], v[114:115], v[122:123] op_sel_hi:[1,0]
	v_pk_mul_f32 v[120:121], v[120:121], v[122:123] op_sel_hi:[1,0]
	v_pk_mul_f32 v[116:117], v[8:9], v[116:117]
	v_pk_mul_f32 v[114:115], v[6:7], v[118:119]
	global_store_dwordx4 v[124:125], v[114:117], off
	s_nop 1
	v_pk_mul_f32 v[116:117], v[4:5], v[126:127]
	v_pk_mul_f32 v[114:115], v[2:3], v[120:121]
	global_store_dwordx4 v[124:125], v[114:117], off offset:512
	s_nop 1
	v_or_b32_e32 v114, 16, v152
	v_ashrrev_i32_e32 v115, 31, v114
	v_mov_b32_e32 v116, 0
	v_mov_b32_e32 v117, 0
	s_nop 0
	s_waitcnt vmcnt(17)
	v_mov_b32_e32 v117, v196
	v_lshlrev_b64 v[114:115], 12, v[114:115]
	v_lshl_add_u64 v[114:115], s[48:49], 0, v[114:115]
	v_lshl_add_u64 v[114:115], v[150:151], 2, v[114:115]
	s_waitcnt lgkmcnt(0)
	v_fmamk_f32 v117, v117, 0x3a800000, v172
	v_rsq_f32_e32 v118, v117
	s_nop 0
	v_pk_mul_f32 v[106:107], v[106:107], v[118:119] op_sel_hi:[1,0]
	v_pk_mul_f32 v[120:121], v[108:109], v[118:119] op_sel_hi:[1,0]
	v_pk_mul_f32 v[110:111], v[110:111], v[118:119] op_sel_hi:[1,0]
	v_pk_mul_f32 v[112:113], v[112:113], v[118:119] op_sel_hi:[1,0]
	v_pk_mul_f32 v[108:109], v[8:9], v[106:107]
	v_pk_mul_f32 v[106:107], v[6:7], v[120:121]
	global_store_dwordx4 v[114:115], v[106:109], off
	s_nop 1
	v_pk_mul_f32 v[108:109], v[4:5], v[110:111]
	v_pk_mul_f32 v[106:107], v[2:3], v[112:113]
	global_store_dwordx4 v[114:115], v[106:109], off offset:512
	s_nop 1
	v_or_b32_e32 v106, 24, v152
	v_ashrrev_i32_e32 v107, 31, v106
	s_nop 0
	s_waitcnt vmcnt(18)
	v_mov_b32_e32 v108, v197
	v_lshlrev_b64 v[106:107], 12, v[106:107]
	v_lshl_add_u64 v[106:107], s[48:49], 0, v[106:107]
	v_lshl_add_u64 v[106:107], v[150:151], 2, v[106:107]
	s_waitcnt lgkmcnt(0)
	v_fmamk_f32 v108, v108, 0x3a800000, v172
	v_rsq_f32_e32 v108, v108
	s_nop 0
	v_pk_mul_f32 v[100:101], v[100:101], v[108:109] op_sel_hi:[1,0]
	v_pk_mul_f32 v[102:103], v[102:103], v[108:109] op_sel_hi:[1,0]
	v_pk_mul_f32 v[110:111], v[98:99], v[108:109] op_sel_hi:[1,0]
	v_pk_mul_f32 v[104:105], v[104:105], v[108:109] op_sel_hi:[1,0]
	v_pk_mul_f32 v[100:101], v[8:9], v[100:101]
	v_pk_mul_f32 v[98:99], v[6:7], v[102:103]
	global_store_dwordx4 v[106:107], v[98:101], off
	s_nop 1
	v_pk_mul_f32 v[100:101], v[4:5], v[110:111]
	v_pk_mul_f32 v[98:99], v[2:3], v[104:105]
	global_store_dwordx4 v[106:107], v[98:101], off offset:512
	s_nop 1
	v_or_b32_e32 v98, 32, v152
	v_ashrrev_i32_e32 v99, 31, v98
	v_mov_b32_e32 v100, 0
	v_mov_b32_e32 v101, 0
	s_nop 0
	s_waitcnt vmcnt(19)
	v_mov_b32_e32 v101, v198
	v_lshlrev_b64 v[98:99], 12, v[98:99]
	v_lshl_add_u64 v[98:99], s[48:49], 0, v[98:99]
	v_lshl_add_u64 v[98:99], v[150:151], 2, v[98:99]
	s_waitcnt lgkmcnt(0)
; __device__ __forceinline__ float rstd_of(float ss) { return __builtin_amdgcn_rsqf(ss * (1.0f / DM) + EPS); }
; __device__ __forceinline__ float atomic_read_f32(float* p) { return __hip_atomic_fetch_add(p, 0.0f, __ATOMIC_RELAXED, __HIP_MEMORY_SCOPE_AGENT); }
;     __device__ __forceinline__ void operator()(pg8::f32x4 (&acc)[2][2][4][2], const Unit& u, int wr, int wc, int fr, int fq) const {
;     ...
;         for (int ai = 0; ai < 2; ++ai)
; #pragma unroll
;             for (int m = 0; m < 4; ++m)
; #pragma unroll
;                 for (int p = 0; p < 2; ++p) { const int row = row0 + ai * HALF + m * 16 + 8 * p + rr; float s = 0.f; if (sl == 0) s = atomic_read_f32(SS2 + row); const float rs = rstd_of(__shfl(s, lane & ~7));
; #pragma unroll
;                     for (int bj = 0; bj < 2; ++bj) *(pg8::f32x4*)(YO + (size_t)row * DM + cbase + bj * HALF) = acc[ai][bj][m][p] * rs * gn[bj]; }
	v_fmamk_f32 v101, v101, 0x3a800000, v172
	v_rsq_f32_e32 v102, v101
	s_nop 0
	v_pk_mul_f32 v[90:91], v[90:91], v[102:103] op_sel_hi:[1,0]
	v_pk_mul_f32 v[104:105], v[92:93], v[102:103] op_sel_hi:[1,0]
	v_pk_mul_f32 v[94:95], v[94:95], v[102:103] op_sel_hi:[1,0]
	v_pk_mul_f32 v[96:97], v[96:97], v[102:103] op_sel_hi:[1,0]
	v_pk_mul_f32 v[92:93], v[8:9], v[90:91]
	v_pk_mul_f32 v[90:91], v[6:7], v[104:105]
	global_store_dwordx4 v[98:99], v[90:93], off
	s_nop 1
	v_pk_mul_f32 v[92:93], v[4:5], v[94:95]
	v_pk_mul_f32 v[90:91], v[2:3], v[96:97]
	global_store_dwordx4 v[98:99], v[90:93], off offset:512
	s_nop 1
	v_or_b32_e32 v90, 40, v152
	v_ashrrev_i32_e32 v91, 31, v90
	s_nop 0
	s_waitcnt vmcnt(20)
	v_mov_b32_e32 v92, v199
	v_lshlrev_b64 v[90:91], 12, v[90:91]
	v_lshl_add_u64 v[90:91], s[48:49], 0, v[90:91]
	v_lshl_add_u64 v[90:91], v[150:151], 2, v[90:91]
	s_waitcnt lgkmcnt(0)
	v_fmamk_f32 v92, v92, 0x3a800000, v172
	v_rsq_f32_e32 v92, v92
	s_nop 0
	v_pk_mul_f32 v[84:85], v[84:85], v[92:93] op_sel_hi:[1,0]
	v_pk_mul_f32 v[86:87], v[86:87], v[92:93] op_sel_hi:[1,0]
	v_pk_mul_f32 v[94:95], v[82:83], v[92:93] op_sel_hi:[1,0]
	v_pk_mul_f32 v[88:89], v[88:89], v[92:93] op_sel_hi:[1,0]
	v_pk_mul_f32 v[84:85], v[8:9], v[84:85]
	v_pk_mul_f32 v[82:83], v[6:7], v[86:87]
	global_store_dwordx4 v[90:91], v[82:85], off
	s_nop 1
	v_pk_mul_f32 v[84:85], v[4:5], v[94:95]
	v_pk_mul_f32 v[82:83], v[2:3], v[88:89]
	global_store_dwordx4 v[90:91], v[82:85], off offset:512
	s_nop 1
	v_or_b32_e32 v82, 48, v152
	v_ashrrev_i32_e32 v83, 31, v82
	v_mov_b32_e32 v84, 0
	v_mov_b32_e32 v85, 0
	s_nop 0
	s_waitcnt vmcnt(21)
	v_mov_b32_e32 v85, v200
	v_lshlrev_b64 v[82:83], 12, v[82:83]
	v_lshl_add_u64 v[82:83], s[48:49], 0, v[82:83]
	v_lshl_add_u64 v[82:83], v[150:151], 2, v[82:83]
	s_waitcnt lgkmcnt(0)
	v_fmamk_f32 v85, v85, 0x3a800000, v172
	v_rsq_f32_e32 v86, v85
	s_nop 0
	v_pk_mul_f32 v[74:75], v[74:75], v[86:87] op_sel_hi:[1,0]
	v_pk_mul_f32 v[88:89], v[76:77], v[86:87] op_sel_hi:[1,0]
	v_pk_mul_f32 v[78:79], v[78:79], v[86:87] op_sel_hi:[1,0]
	v_pk_mul_f32 v[80:81], v[80:81], v[86:87] op_sel_hi:[1,0]
	v_pk_mul_f32 v[76:77], v[8:9], v[74:75]
	v_pk_mul_f32 v[74:75], v[6:7], v[88:89]
	global_store_dwordx4 v[82:83], v[74:77], off
	s_nop 1
	v_pk_mul_f32 v[76:77], v[4:5], v[78:79]
	v_pk_mul_f32 v[74:75], v[2:3], v[80:81]
	global_store_dwordx4 v[82:83], v[74:77], off offset:512
	s_nop 1
	v_or_b32_e32 v74, 56, v152
	v_ashrrev_i32_e32 v75, 31, v74
	s_nop 0
	s_waitcnt vmcnt(22)
	v_mov_b32_e32 v76, v201
	v_lshlrev_b64 v[74:75], 12, v[74:75]
	v_lshl_add_u64 v[74:75], s[48:49], 0, v[74:75]
	v_lshl_add_u64 v[74:75], v[150:151], 2, v[74:75]
	s_waitcnt lgkmcnt(0)
	v_fmamk_f32 v76, v76, 0x3a800000, v172
	v_rsq_f32_e32 v76, v76
	s_nop 0
	v_pk_mul_f32 v[68:69], v[68:69], v[76:77] op_sel_hi:[1,0]
	v_pk_mul_f32 v[70:71], v[70:71], v[76:77] op_sel_hi:[1,0]
	v_pk_mul_f32 v[78:79], v[66:67], v[76:77] op_sel_hi:[1,0]
	v_pk_mul_f32 v[72:73], v[72:73], v[76:77] op_sel_hi:[1,0]
	v_pk_mul_f32 v[68:69], v[8:9], v[68:69]
	v_pk_mul_f32 v[66:67], v[6:7], v[70:71]
	global_store_dwordx4 v[74:75], v[66:69], off
	s_nop 1
	v_pk_mul_f32 v[68:69], v[4:5], v[78:79]
	v_pk_mul_f32 v[66:67], v[2:3], v[72:73]
	global_store_dwordx4 v[74:75], v[66:69], off offset:512
	s_nop 1
	v_add_u32_e32 v66, 0x80, v152
	v_ashrrev_i32_e32 v67, 31, v66
	v_mov_b32_e32 v68, 0
	v_mov_b32_e32 v69, 0
	s_nop 0
	s_waitcnt vmcnt(23)
	v_mov_b32_e32 v69, v202
	v_lshlrev_b64 v[66:67], 12, v[66:67]
	v_lshl_add_u64 v[66:67], s[48:49], 0, v[66:67]
	v_lshl_add_u64 v[66:67], v[150:151], 2, v[66:67]
	s_waitcnt lgkmcnt(0)
	v_fmamk_f32 v69, v69, 0x3a800000, v172
	v_rsq_f32_e32 v70, v69
	s_nop 0
	v_pk_mul_f32 v[58:59], v[58:59], v[70:71] op_sel_hi:[1,0]
	v_pk_mul_f32 v[72:73], v[60:61], v[70:71] op_sel_hi:[1,0]
	v_pk_mul_f32 v[62:63], v[62:63], v[70:71] op_sel_hi:[1,0]
	v_pk_mul_f32 v[64:65], v[64:65], v[70:71] op_sel_hi:[1,0]
	v_pk_mul_f32 v[60:61], v[8:9], v[58:59]
	v_pk_mul_f32 v[58:59], v[6:7], v[72:73]
	global_store_dwordx4 v[66:67], v[58:61], off
	s_nop 1
	v_pk_mul_f32 v[60:61], v[4:5], v[62:63]
	v_pk_mul_f32 v[58:59], v[2:3], v[64:65]
	global_store_dwordx4 v[66:67], v[58:61], off offset:512
	s_nop 1
	v_add_u32_e32 v58, 0x88, v152
	v_ashrrev_i32_e32 v59, 31, v58
	s_nop 0
	s_waitcnt vmcnt(24)
	v_mov_b32_e32 v60, v203
	v_lshlrev_b64 v[58:59], 12, v[58:59]
	v_lshl_add_u64 v[58:59], s[48:49], 0, v[58:59]
	v_lshl_add_u64 v[58:59], v[150:151], 2, v[58:59]
	s_waitcnt lgkmcnt(0)
	v_fmamk_f32 v60, v60, 0x3a800000, v172
	v_rsq_f32_e32 v60, v60
	s_nop 0
	v_pk_mul_f32 v[52:53], v[52:53], v[60:61] op_sel_hi:[1,0]
	v_pk_mul_f32 v[54:55], v[54:55], v[60:61] op_sel_hi:[1,0]
	v_pk_mul_f32 v[62:63], v[50:51], v[60:61] op_sel_hi:[1,0]
	v_pk_mul_f32 v[56:57], v[56:57], v[60:61] op_sel_hi:[1,0]
	v_pk_mul_f32 v[52:53], v[8:9], v[52:53]
	v_pk_mul_f32 v[50:51], v[6:7], v[54:55]
	global_store_dwordx4 v[58:59], v[50:53], off
	s_nop 1
	v_pk_mul_f32 v[52:53], v[4:5], v[62:63]
	v_pk_mul_f32 v[50:51], v[2:3], v[56:57]
	global_store_dwordx4 v[58:59], v[50:53], off offset:512
	s_nop 1
	v_add_u32_e32 v50, 0x90, v152
	v_ashrrev_i32_e32 v51, 31, v50
	v_mov_b32_e32 v52, 0
	v_mov_b32_e32 v53, 0
	s_nop 0
	s_waitcnt vmcnt(25)
; __device__ __forceinline__ float rstd_of(float ss) { return __builtin_amdgcn_rsqf(ss * (1.0f / DM) + EPS); }
; __device__ __forceinline__ float atomic_read_f32(float* p) { return __hip_atomic_fetch_add(p, 0.0f, __ATOMIC_RELAXED, __HIP_MEMORY_SCOPE_AGENT); }
;     __device__ __forceinline__ void operator()(pg8::f32x4 (&acc)[2][2][4][2], const Unit& u, int wr, int wc, int fr, int fq) const {
;     ...
;         for (int ai = 0; ai < 2; ++ai)
; #pragma unroll
;             for (int m = 0; m < 4; ++m)
; #pragma unroll
;                 for (int p = 0; p < 2; ++p) { const int row = row0 + ai * HALF + m * 16 + 8 * p + rr; float s = 0.f; if (sl == 0) s = atomic_read_f32(SS2 + row); const float rs = rstd_of(__shfl(s, lane & ~7));
; #pragma unroll
;                     for (int bj = 0; bj < 2; ++bj) *(pg8::f32x4*)(YO + (size_t)row * DM + cbase + bj * HALF) = acc[ai][bj][m][p] * rs * gn[bj]; }
	v_mov_b32_e32 v53, v204
	v_lshlrev_b64 v[50:51], 12, v[50:51]
	v_lshl_add_u64 v[50:51], s[48:49], 0, v[50:51]
	v_lshl_add_u64 v[50:51], v[150:151], 2, v[50:51]
	s_waitcnt lgkmcnt(0)
	v_fmamk_f32 v53, v53, 0x3a800000, v172
	v_rsq_f32_e32 v54, v53
	s_nop 0
	v_pk_mul_f32 v[42:43], v[42:43], v[54:55] op_sel_hi:[1,0]
	v_pk_mul_f32 v[56:57], v[44:45], v[54:55] op_sel_hi:[1,0]
	v_pk_mul_f32 v[46:47], v[46:47], v[54:55] op_sel_hi:[1,0]
	v_pk_mul_f32 v[48:49], v[48:49], v[54:55] op_sel_hi:[1,0]
	v_pk_mul_f32 v[44:45], v[8:9], v[42:43]
	v_pk_mul_f32 v[42:43], v[6:7], v[56:57]
	global_store_dwordx4 v[50:51], v[42:45], off
	s_nop 1
	v_pk_mul_f32 v[44:45], v[4:5], v[46:47]
	v_pk_mul_f32 v[42:43], v[2:3], v[48:49]
	global_store_dwordx4 v[50:51], v[42:45], off offset:512
	s_nop 1
	v_add_u32_e32 v42, 0x98, v152
	v_ashrrev_i32_e32 v43, 31, v42
	s_nop 0
	s_waitcnt vmcnt(26)
	v_mov_b32_e32 v44, v205
	v_lshlrev_b64 v[42:43], 12, v[42:43]
	v_lshl_add_u64 v[42:43], s[48:49], 0, v[42:43]
	v_lshl_add_u64 v[42:43], v[150:151], 2, v[42:43]
	s_waitcnt lgkmcnt(0)
	v_fmamk_f32 v44, v44, 0x3a800000, v172
	v_rsq_f32_e32 v44, v44
	s_nop 0
	v_pk_mul_f32 v[36:37], v[36:37], v[44:45] op_sel_hi:[1,0]
	v_pk_mul_f32 v[38:39], v[38:39], v[44:45] op_sel_hi:[1,0]
	v_pk_mul_f32 v[46:47], v[34:35], v[44:45] op_sel_hi:[1,0]
	v_pk_mul_f32 v[40:41], v[40:41], v[44:45] op_sel_hi:[1,0]
	v_pk_mul_f32 v[36:37], v[8:9], v[36:37]
	v_pk_mul_f32 v[34:35], v[6:7], v[38:39]
	global_store_dwordx4 v[42:43], v[34:37], off
	s_nop 1
	v_pk_mul_f32 v[36:37], v[4:5], v[46:47]
	v_pk_mul_f32 v[34:35], v[2:3], v[40:41]
	global_store_dwordx4 v[42:43], v[34:37], off offset:512
	s_nop 1
	v_add_u32_e32 v34, 0xa0, v152
	v_ashrrev_i32_e32 v35, 31, v34
	v_mov_b32_e32 v36, 0
	v_mov_b32_e32 v37, 0
	s_nop 0
	s_waitcnt vmcnt(27)
	v_mov_b32_e32 v37, v206
	v_lshlrev_b64 v[34:35], 12, v[34:35]
	v_lshl_add_u64 v[34:35], s[48:49], 0, v[34:35]
	v_lshl_add_u64 v[34:35], v[150:151], 2, v[34:35]
	s_waitcnt lgkmcnt(0)
	v_fmamk_f32 v37, v37, 0x3a800000, v172
	v_rsq_f32_e32 v38, v37
	s_nop 0
	v_pk_mul_f32 v[26:27], v[26:27], v[38:39] op_sel_hi:[1,0]
	v_pk_mul_f32 v[40:41], v[28:29], v[38:39] op_sel_hi:[1,0]
	v_pk_mul_f32 v[30:31], v[30:31], v[38:39] op_sel_hi:[1,0]
	v_pk_mul_f32 v[32:33], v[32:33], v[38:39] op_sel_hi:[1,0]
	v_pk_mul_f32 v[28:29], v[8:9], v[26:27]
	v_pk_mul_f32 v[26:27], v[6:7], v[40:41]
	global_store_dwordx4 v[34:35], v[26:29], off
	s_nop 1
	v_pk_mul_f32 v[28:29], v[4:5], v[30:31]
	v_pk_mul_f32 v[26:27], v[2:3], v[32:33]
	global_store_dwordx4 v[34:35], v[26:29], off offset:512
	s_nop 1
	v_add_u32_e32 v26, 0xa8, v152
	v_ashrrev_i32_e32 v27, 31, v26
	s_nop 0
	s_waitcnt vmcnt(28)
	v_mov_b32_e32 v28, v207
	v_lshlrev_b64 v[26:27], 12, v[26:27]
	v_lshl_add_u64 v[26:27], s[48:49], 0, v[26:27]
	v_lshl_add_u64 v[26:27], v[150:151], 2, v[26:27]
	s_waitcnt lgkmcnt(0)
	v_fmamk_f32 v28, v28, 0x3a800000, v172
	v_rsq_f32_e32 v28, v28
	s_nop 0
	v_pk_mul_f32 v[20:21], v[20:21], v[28:29] op_sel_hi:[1,0]
	v_pk_mul_f32 v[22:23], v[22:23], v[28:29] op_sel_hi:[1,0]
	v_pk_mul_f32 v[30:31], v[18:19], v[28:29] op_sel_hi:[1,0]
	v_pk_mul_f32 v[24:25], v[24:25], v[28:29] op_sel_hi:[1,0]
	v_pk_mul_f32 v[20:21], v[8:9], v[20:21]
	v_pk_mul_f32 v[18:19], v[6:7], v[22:23]
	global_store_dwordx4 v[26:27], v[18:21], off
	s_nop 1
	v_pk_mul_f32 v[20:21], v[4:5], v[30:31]
	v_pk_mul_f32 v[18:19], v[2:3], v[24:25]
	global_store_dwordx4 v[26:27], v[18:21], off offset:512
	s_nop 1
	v_add_u32_e32 v18, 0xb0, v152
	v_ashrrev_i32_e32 v19, 31, v18
	v_mov_b32_e32 v20, 0
	v_mov_b32_e32 v21, 0
	s_nop 0
	s_waitcnt vmcnt(29)
	v_mov_b32_e32 v21, v208
	v_lshlrev_b64 v[18:19], 12, v[18:19]
	v_lshl_add_u64 v[18:19], s[48:49], 0, v[18:19]
	v_lshl_add_u64 v[18:19], v[150:151], 2, v[18:19]
	s_waitcnt lgkmcnt(0)
	v_fmamk_f32 v21, v21, 0x3a800000, v172
	v_rsq_f32_e32 v22, v21
	s_nop 0
	v_pk_mul_f32 v[24:25], v[158:159], v[22:23] op_sel_hi:[1,0]
	v_pk_mul_f32 v[26:27], v[160:161], v[22:23] op_sel_hi:[1,0]
	v_pk_mul_f32 v[28:29], v[162:163], v[22:23] op_sel_hi:[1,0]
	v_pk_mul_f32 v[30:31], v[164:165], v[22:23] op_sel_hi:[1,0]
	v_pk_mul_f32 v[24:25], v[8:9], v[24:25]
	v_pk_mul_f32 v[22:23], v[6:7], v[26:27]
	global_store_dwordx4 v[18:19], v[22:25], off
	s_nop 1
	v_pk_mul_f32 v[24:25], v[4:5], v[28:29]
	v_pk_mul_f32 v[22:23], v[2:3], v[30:31]
	global_store_dwordx4 v[18:19], v[22:25], off offset:512
	v_add_u32_e32 v18, 0xb8, v152
	v_ashrrev_i32_e32 v19, 31, v18
	s_nop 0
	s_waitcnt vmcnt(30)
	v_mov_b32_e32 v20, v209
	v_lshlrev_b64 v[18:19], 12, v[18:19]
	v_lshl_add_u64 v[18:19], s[48:49], 0, v[18:19]
	v_lshl_add_u64 v[18:19], v[150:151], 2, v[18:19]
	s_and_b64 vcc, exec, s[10:11]
	s_waitcnt lgkmcnt(0)
	v_fmamk_f32 v20, v20, 0x3a800000, v172
	v_rsq_f32_e32 v20, v20
	s_mov_b64 s[4:5], -1
	v_pk_mul_f32 v[12:13], v[12:13], v[20:21] op_sel_hi:[1,0]
	v_pk_mul_f32 v[14:15], v[14:15], v[20:21] op_sel_hi:[1,0]
	v_pk_mul_f32 v[10:11], v[10:11], v[20:21] op_sel_hi:[1,0]
	v_pk_mul_f32 v[16:17], v[16:17], v[20:21] op_sel_hi:[1,0]
	v_pk_mul_f32 v[8:9], v[8:9], v[12:13]
	v_pk_mul_f32 v[6:7], v[6:7], v[14:15]
	v_pk_mul_f32 v[4:5], v[4:5], v[10:11]
	v_pk_mul_f32 v[2:3], v[2:3], v[16:17]
	global_store_dwordx4 v[18:19], v[6:9], off
	global_store_dwordx4 v[18:19], v[2:5], off offset:512
	s_cbranch_vccnz .LBB0_1056
	s_andn2_b64 vcc, exec, s[22:23]
	s_cbranch_vccnz .LBB0_1055
	s_barrier
	s_branch .LBB0_1055
